# QKV projection epilogue (rope + scale) de-serialised: 8 ssq loads and a rolling window of rope quads up front, one counted wait per row group, stores back to back
# speedup vs baseline: 1.0005x; 1.0005x over previous
.LBB0_691:
	v_lshl_add_u32 v246, s6, 8, v146
	v_lshlrev_b32_e32 v247, 2, v246
	global_load_dword v160, v247, s[12:13] offset:0
	global_load_dword v162, v247, s[12:13] offset:64
	global_load_dword v164, v247, s[12:13] offset:128
	global_load_dword v166, v247, s[12:13] offset:192
	global_load_dword v170, v247, s[12:13] offset:512
	global_load_dword v172, v247, s[12:13] offset:576
	global_load_dword v174, v247, s[12:13] offset:640
	global_load_dword v176, v247, s[12:13] offset:704
	v_lshlrev_b32_e32 v142, 8, v246
	v_and_b32_e32 v142, 0xfcf00, v142
	v_mov_b32_e32 v143, 0
	v_lshl_add_u64 v[142:143], v[130:131], 0, v[142:143]
	global_load_dwordx4 v[178:181], v[142:143], off
	global_load_dwordx4 v[182:185], v[142:143], off offset:16
	s_mov_b64 s[6:7], 0x1000
	v_lshl_add_u64 v[144:145], v[142:143], 0, s[6:7]
	global_load_dwordx4 v[204:207], v[144:145], off
	global_load_dwordx4 v[208:211], v[144:145], off offset:16
	s_mov_b64 s[6:7], 0x2000
	v_lshl_add_u64 v[144:145], v[142:143], 0, s[6:7]
	global_load_dwordx4 v[212:215], v[144:145], off
	global_load_dwordx4 v[216:219], v[144:145], off offset:16
	s_mov_b64 s[6:7], 0x3000
	v_lshl_add_u64 v[144:145], v[142:143], 0, s[6:7]
	global_load_dwordx4 v[238:241], v[144:145], off
	global_load_dwordx4 v[242:245], v[144:145], off offset:16
	v_lshlrev_b32_e32 v249, s62, v246
	s_lshl_b32 s63, s50, 1
	s_add_i32 s63, s63, s60
	v_add3_u32 v249, v249, s63, v128
	s_lshl_b32 s16, s46, 5
	s_waitcnt vmcnt(8)
	v_fmamk_f32 v160, v160, 0x3a000000, v151
	v_fmamk_f32 v162, v162, 0x3a000000, v151
	v_fmamk_f32 v164, v164, 0x3a000000, v151
	v_fmamk_f32 v166, v166, 0x3a000000, v151
	v_fmamk_f32 v170, v170, 0x3a000000, v151
	v_fmamk_f32 v172, v172, 0x3a000000, v151
	v_fmamk_f32 v174, v174, 0x3a000000, v151
	v_fmamk_f32 v176, v176, 0x3a000000, v151
	v_mul_f32_e32 v161, 0x4b800000, v160
	v_mul_f32_e32 v163, 0x4b800000, v162
	v_mul_f32_e32 v165, 0x4b800000, v164
	v_mul_f32_e32 v167, 0x4b800000, v166
	v_mul_f32_e32 v171, 0x4b800000, v170
	v_mul_f32_e32 v173, 0x4b800000, v172
	v_mul_f32_e32 v175, 0x4b800000, v174
	v_mul_f32_e32 v177, 0x4b800000, v176
	v_cmp_gt_f32_e32 vcc, s80, v160
	v_cmp_gt_f32_e64 s[6:7], s80, v162
	s_nop 1
	v_cndmask_b32_e32 v160, v160, v161, vcc
	v_cndmask_b32_e64 v162, v162, v163, s[6:7]
	v_rsq_f32_e32 v160, v160
	v_rsq_f32_e32 v162, v162
	s_nop 0
	v_mul_f32_e32 v161, 0x45800000, v160
	v_mul_f32_e32 v163, 0x45800000, v162
	v_cndmask_b32_e32 v160, v160, v161, vcc
	v_cndmask_b32_e64 v162, v162, v163, s[6:7]
	v_mul_f32_e32 v160, s31, v160
	v_mul_f32_e32 v162, s31, v162
	v_cmp_gt_f32_e32 vcc, s80, v164
	v_cmp_gt_f32_e64 s[6:7], s80, v166
	s_nop 1
	v_cndmask_b32_e32 v164, v164, v165, vcc
	v_cndmask_b32_e64 v166, v166, v167, s[6:7]
	v_rsq_f32_e32 v164, v164
	v_rsq_f32_e32 v166, v166
	s_nop 0
	v_mul_f32_e32 v165, 0x45800000, v164
	v_mul_f32_e32 v167, 0x45800000, v166
	v_cndmask_b32_e32 v164, v164, v165, vcc
	v_cndmask_b32_e64 v166, v166, v167, s[6:7]
	v_mul_f32_e32 v164, s31, v164
	v_mul_f32_e32 v166, s31, v166
	v_cmp_gt_f32_e32 vcc, s80, v170
	v_cmp_gt_f32_e64 s[6:7], s80, v172
	s_nop 1
	v_cndmask_b32_e32 v170, v170, v171, vcc
	v_cndmask_b32_e64 v172, v172, v173, s[6:7]
	v_rsq_f32_e32 v170, v170
	v_rsq_f32_e32 v172, v172
	s_nop 0
	v_mul_f32_e32 v171, 0x45800000, v170
	v_mul_f32_e32 v173, 0x45800000, v172
	v_cndmask_b32_e32 v170, v170, v171, vcc
	v_cndmask_b32_e64 v172, v172, v173, s[6:7]
	v_mul_f32_e32 v170, s31, v170
	v_mul_f32_e32 v172, s31, v172
	v_cmp_gt_f32_e32 vcc, s80, v174
	v_cmp_gt_f32_e64 s[6:7], s80, v176
	s_nop 1
	v_cndmask_b32_e32 v174, v174, v175, vcc
	v_cndmask_b32_e64 v176, v176, v177, s[6:7]
	v_rsq_f32_e32 v174, v174
	v_rsq_f32_e32 v176, v176
	s_nop 0
	v_mul_f32_e32 v175, 0x45800000, v174
	v_mul_f32_e32 v177, 0x45800000, v176
	v_cndmask_b32_e32 v174, v174, v175, vcc
	v_cndmask_b32_e64 v176, v176, v177, s[6:7]
	v_mul_f32_e32 v174, s31, v174
	v_mul_f32_e32 v176, s31, v176
	v_mov_b32_e32 v236, v249
	s_waitcnt vmcnt(6)
	v_pk_mul_f32 v[124:125], v[124:125], v[160:161] op_sel_hi:[1,0]
	v_pk_mul_f32 v[126:127], v[126:127], v[160:161] op_sel_hi:[1,0]
	v_pk_mul_f32 v[120:121], v[120:121], v[160:161] op_sel_hi:[1,0]
	v_pk_mul_f32 v[122:123], v[122:123], v[160:161] op_sel_hi:[1,0]
	v_pk_mul_f32 v[250:251], v[178:179], v[124:125]
	v_pk_mul_f32 v[252:253], v[180:181], v[126:127]
	v_pk_mul_f32 v[254:255], v[182:183], v[120:121]
	v_pk_mul_f32 v[232:233], v[184:185], v[122:123]
	v_pk_mul_f32 v[124:125], v[178:179], v[124:125] op_sel:[0,1] op_sel_hi:[1,0]
	v_pk_mul_f32 v[126:127], v[180:181], v[126:127] op_sel:[0,1] op_sel_hi:[1,0]
	v_pk_mul_f32 v[120:121], v[182:183], v[120:121] op_sel:[0,1] op_sel_hi:[1,0]
	v_pk_mul_f32 v[122:123], v[184:185], v[122:123] op_sel:[0,1] op_sel_hi:[1,0]
	v_sub_f32_e32 v250, v250, v251
	v_add_f32_e32 v124, v124, v125
	v_sub_f32_e32 v252, v252, v253
	v_add_f32_e32 v126, v126, v127
	v_sub_f32_e32 v254, v254, v255
	v_add_f32_e32 v120, v120, v121
	v_sub_f32_e32 v232, v232, v233
	v_add_f32_e32 v122, v122, v123
	v_cvt_pk_bf16_f32 v124, v250, v124
	v_cvt_pk_bf16_f32 v125, v252, v126
	v_cvt_pk_bf16_f32 v126, v254, v120
	v_cvt_pk_bf16_f32 v127, v232, v122
	global_store_dwordx4 v236, v[124:127], s[54:55]
	v_pk_mul_f32 v[116:117], v[116:117], v[160:161] op_sel_hi:[1,0]
	v_pk_mul_f32 v[118:119], v[118:119], v[160:161] op_sel_hi:[1,0]
	v_pk_mul_f32 v[112:113], v[112:113], v[160:161] op_sel_hi:[1,0]
	v_pk_mul_f32 v[114:115], v[114:115], v[160:161] op_sel_hi:[1,0]
	v_pk_mul_f32 v[250:251], v[178:179], v[116:117]
	v_pk_mul_f32 v[252:253], v[180:181], v[118:119]
	v_pk_mul_f32 v[254:255], v[182:183], v[112:113]
	v_pk_mul_f32 v[232:233], v[184:185], v[114:115]
	v_pk_mul_f32 v[116:117], v[178:179], v[116:117] op_sel:[0,1] op_sel_hi:[1,0]
	v_pk_mul_f32 v[118:119], v[180:181], v[118:119] op_sel:[0,1] op_sel_hi:[1,0]
	v_pk_mul_f32 v[112:113], v[182:183], v[112:113] op_sel:[0,1] op_sel_hi:[1,0]
	v_pk_mul_f32 v[114:115], v[184:185], v[114:115] op_sel:[0,1] op_sel_hi:[1,0]
	v_sub_f32_e32 v250, v250, v251
	v_add_f32_e32 v116, v116, v117
	v_sub_f32_e32 v252, v252, v253
	v_add_f32_e32 v118, v118, v119
	v_sub_f32_e32 v254, v254, v255
	v_add_f32_e32 v112, v112, v113
	v_sub_f32_e32 v232, v232, v233
	v_add_f32_e32 v114, v114, v115
	v_cvt_pk_bf16_f32 v116, v250, v116
	v_cvt_pk_bf16_f32 v117, v252, v118
	v_cvt_pk_bf16_f32 v118, v254, v112
	v_cvt_pk_bf16_f32 v119, v232, v114
	global_store_dwordx4 v236, v[116:119], s[54:55] offset:256
	s_mov_b64 s[6:7], 0x8000
	v_lshl_add_u64 v[144:145], v[142:143], 0, s[6:7]
	global_load_dwordx4 v[178:181], v[144:145], off
	global_load_dwordx4 v[182:185], v[144:145], off offset:16
	s_mul_i32 s61, s16, 1
	v_add_u32_e32 v194, s61, v249
	s_waitcnt vmcnt(8)
	v_pk_mul_f32 v[108:109], v[108:109], v[162:163] op_sel_hi:[1,0]
	v_pk_mul_f32 v[110:111], v[110:111], v[162:163] op_sel_hi:[1,0]
	v_pk_mul_f32 v[104:105], v[104:105], v[162:163] op_sel_hi:[1,0]
	v_pk_mul_f32 v[106:107], v[106:107], v[162:163] op_sel_hi:[1,0]
	v_pk_mul_f32 v[250:251], v[204:205], v[108:109]
	v_pk_mul_f32 v[252:253], v[206:207], v[110:111]
	v_pk_mul_f32 v[254:255], v[208:209], v[104:105]
	v_pk_mul_f32 v[232:233], v[210:211], v[106:107]
	v_pk_mul_f32 v[108:109], v[204:205], v[108:109] op_sel:[0,1] op_sel_hi:[1,0]
	v_pk_mul_f32 v[110:111], v[206:207], v[110:111] op_sel:[0,1] op_sel_hi:[1,0]
	v_pk_mul_f32 v[104:105], v[208:209], v[104:105] op_sel:[0,1] op_sel_hi:[1,0]
	v_pk_mul_f32 v[106:107], v[210:211], v[106:107] op_sel:[0,1] op_sel_hi:[1,0]
	v_sub_f32_e32 v250, v250, v251
	v_add_f32_e32 v108, v108, v109
	v_sub_f32_e32 v252, v252, v253
	v_add_f32_e32 v110, v110, v111
	v_sub_f32_e32 v254, v254, v255
	v_add_f32_e32 v104, v104, v105
	v_sub_f32_e32 v232, v232, v233
	v_add_f32_e32 v106, v106, v107
	v_cvt_pk_bf16_f32 v108, v250, v108
	v_cvt_pk_bf16_f32 v109, v252, v110
	v_cvt_pk_bf16_f32 v110, v254, v104
	v_cvt_pk_bf16_f32 v111, v232, v106
	global_store_dwordx4 v194, v[108:111], s[54:55]
	v_pk_mul_f32 v[100:101], v[100:101], v[162:163] op_sel_hi:[1,0]
	v_pk_mul_f32 v[102:103], v[102:103], v[162:163] op_sel_hi:[1,0]
	v_pk_mul_f32 v[96:97], v[96:97], v[162:163] op_sel_hi:[1,0]
	v_pk_mul_f32 v[98:99], v[98:99], v[162:163] op_sel_hi:[1,0]
	v_pk_mul_f32 v[250:251], v[204:205], v[100:101]
	v_pk_mul_f32 v[252:253], v[206:207], v[102:103]
	v_pk_mul_f32 v[254:255], v[208:209], v[96:97]
	v_pk_mul_f32 v[232:233], v[210:211], v[98:99]
	v_pk_mul_f32 v[100:101], v[204:205], v[100:101] op_sel:[0,1] op_sel_hi:[1,0]
	v_pk_mul_f32 v[102:103], v[206:207], v[102:103] op_sel:[0,1] op_sel_hi:[1,0]
	v_pk_mul_f32 v[96:97], v[208:209], v[96:97] op_sel:[0,1] op_sel_hi:[1,0]
	v_pk_mul_f32 v[98:99], v[210:211], v[98:99] op_sel:[0,1] op_sel_hi:[1,0]
	v_sub_f32_e32 v250, v250, v251
	v_add_f32_e32 v100, v100, v101
	v_sub_f32_e32 v252, v252, v253
	v_add_f32_e32 v102, v102, v103
	v_sub_f32_e32 v254, v254, v255
	v_add_f32_e32 v96, v96, v97
	v_sub_f32_e32 v232, v232, v233
	v_add_f32_e32 v98, v98, v99
	v_cvt_pk_bf16_f32 v100, v250, v100
	v_cvt_pk_bf16_f32 v101, v252, v102
	v_cvt_pk_bf16_f32 v102, v254, v96
	v_cvt_pk_bf16_f32 v103, v232, v98
	global_store_dwordx4 v194, v[100:103], s[54:55] offset:256
	s_mov_b64 s[6:7], 0x9000
	v_lshl_add_u64 v[144:145], v[142:143], 0, s[6:7]
	global_load_dwordx4 v[204:207], v[144:145], off
	global_load_dwordx4 v[208:211], v[144:145], off offset:16
	s_mul_i32 s61, s16, 2
	v_add_u32_e32 v195, s61, v249
	s_waitcnt vmcnt(10)
	v_pk_mul_f32 v[92:93], v[92:93], v[164:165] op_sel_hi:[1,0]
	v_pk_mul_f32 v[94:95], v[94:95], v[164:165] op_sel_hi:[1,0]
	v_pk_mul_f32 v[88:89], v[88:89], v[164:165] op_sel_hi:[1,0]
	v_pk_mul_f32 v[90:91], v[90:91], v[164:165] op_sel_hi:[1,0]
	v_pk_mul_f32 v[250:251], v[212:213], v[92:93]
	v_pk_mul_f32 v[252:253], v[214:215], v[94:95]
	v_pk_mul_f32 v[254:255], v[216:217], v[88:89]
	v_pk_mul_f32 v[232:233], v[218:219], v[90:91]
	v_pk_mul_f32 v[92:93], v[212:213], v[92:93] op_sel:[0,1] op_sel_hi:[1,0]
	v_pk_mul_f32 v[94:95], v[214:215], v[94:95] op_sel:[0,1] op_sel_hi:[1,0]
	v_pk_mul_f32 v[88:89], v[216:217], v[88:89] op_sel:[0,1] op_sel_hi:[1,0]
	v_pk_mul_f32 v[90:91], v[218:219], v[90:91] op_sel:[0,1] op_sel_hi:[1,0]
	v_sub_f32_e32 v250, v250, v251
	v_add_f32_e32 v92, v92, v93
	v_sub_f32_e32 v252, v252, v253
	v_add_f32_e32 v94, v94, v95
	v_sub_f32_e32 v254, v254, v255
	v_add_f32_e32 v88, v88, v89
	v_sub_f32_e32 v232, v232, v233
	v_add_f32_e32 v90, v90, v91
	v_cvt_pk_bf16_f32 v92, v250, v92
	v_cvt_pk_bf16_f32 v93, v252, v94
	v_cvt_pk_bf16_f32 v94, v254, v88
	v_cvt_pk_bf16_f32 v95, v232, v90
	global_store_dwordx4 v195, v[92:95], s[54:55]
	v_pk_mul_f32 v[84:85], v[84:85], v[164:165] op_sel_hi:[1,0]
	v_pk_mul_f32 v[86:87], v[86:87], v[164:165] op_sel_hi:[1,0]
	v_pk_mul_f32 v[80:81], v[80:81], v[164:165] op_sel_hi:[1,0]
	v_pk_mul_f32 v[82:83], v[82:83], v[164:165] op_sel_hi:[1,0]
	v_pk_mul_f32 v[250:251], v[212:213], v[84:85]
	v_pk_mul_f32 v[252:253], v[214:215], v[86:87]
	v_pk_mul_f32 v[254:255], v[216:217], v[80:81]
	v_pk_mul_f32 v[232:233], v[218:219], v[82:83]
	v_pk_mul_f32 v[84:85], v[212:213], v[84:85] op_sel:[0,1] op_sel_hi:[1,0]
	v_pk_mul_f32 v[86:87], v[214:215], v[86:87] op_sel:[0,1] op_sel_hi:[1,0]
	v_pk_mul_f32 v[80:81], v[216:217], v[80:81] op_sel:[0,1] op_sel_hi:[1,0]
	v_pk_mul_f32 v[82:83], v[218:219], v[82:83] op_sel:[0,1] op_sel_hi:[1,0]
	v_sub_f32_e32 v250, v250, v251
	v_add_f32_e32 v84, v84, v85
	v_sub_f32_e32 v252, v252, v253
	v_add_f32_e32 v86, v86, v87
	v_sub_f32_e32 v254, v254, v255
	v_add_f32_e32 v80, v80, v81
	v_sub_f32_e32 v232, v232, v233
	v_add_f32_e32 v82, v82, v83
	v_cvt_pk_bf16_f32 v84, v250, v84
	v_cvt_pk_bf16_f32 v85, v252, v86
	v_cvt_pk_bf16_f32 v86, v254, v80
	v_cvt_pk_bf16_f32 v87, v232, v82
	global_store_dwordx4 v195, v[84:87], s[54:55] offset:256
	s_mov_b64 s[6:7], 0xa000
	v_lshl_add_u64 v[144:145], v[142:143], 0, s[6:7]
	global_load_dwordx4 v[212:215], v[144:145], off
	global_load_dwordx4 v[216:219], v[144:145], off offset:16
	s_mul_i32 s61, s16, 3
	v_add_u32_e32 v196, s61, v249
	s_waitcnt vmcnt(12)
	v_pk_mul_f32 v[76:77], v[76:77], v[166:167] op_sel_hi:[1,0]
	v_pk_mul_f32 v[78:79], v[78:79], v[166:167] op_sel_hi:[1,0]
	v_pk_mul_f32 v[72:73], v[72:73], v[166:167] op_sel_hi:[1,0]
	v_pk_mul_f32 v[74:75], v[74:75], v[166:167] op_sel_hi:[1,0]
	v_pk_mul_f32 v[250:251], v[238:239], v[76:77]
	v_pk_mul_f32 v[252:253], v[240:241], v[78:79]
	v_pk_mul_f32 v[254:255], v[242:243], v[72:73]
	v_pk_mul_f32 v[232:233], v[244:245], v[74:75]
	v_pk_mul_f32 v[76:77], v[238:239], v[76:77] op_sel:[0,1] op_sel_hi:[1,0]
	v_pk_mul_f32 v[78:79], v[240:241], v[78:79] op_sel:[0,1] op_sel_hi:[1,0]
	v_pk_mul_f32 v[72:73], v[242:243], v[72:73] op_sel:[0,1] op_sel_hi:[1,0]
	v_pk_mul_f32 v[74:75], v[244:245], v[74:75] op_sel:[0,1] op_sel_hi:[1,0]
	v_sub_f32_e32 v250, v250, v251
	v_add_f32_e32 v76, v76, v77
	v_sub_f32_e32 v252, v252, v253
	v_add_f32_e32 v78, v78, v79
	v_sub_f32_e32 v254, v254, v255
	v_add_f32_e32 v72, v72, v73
	v_sub_f32_e32 v232, v232, v233
	v_add_f32_e32 v74, v74, v75
	v_cvt_pk_bf16_f32 v76, v250, v76
	v_cvt_pk_bf16_f32 v77, v252, v78
	v_cvt_pk_bf16_f32 v78, v254, v72
	v_cvt_pk_bf16_f32 v79, v232, v74
	global_store_dwordx4 v196, v[76:79], s[54:55]
	v_pk_mul_f32 v[68:69], v[68:69], v[166:167] op_sel_hi:[1,0]
	v_pk_mul_f32 v[70:71], v[70:71], v[166:167] op_sel_hi:[1,0]
	v_pk_mul_f32 v[64:65], v[64:65], v[166:167] op_sel_hi:[1,0]
	v_pk_mul_f32 v[66:67], v[66:67], v[166:167] op_sel_hi:[1,0]
	v_pk_mul_f32 v[250:251], v[238:239], v[68:69]
	v_pk_mul_f32 v[252:253], v[240:241], v[70:71]
	v_pk_mul_f32 v[254:255], v[242:243], v[64:65]
	v_pk_mul_f32 v[232:233], v[244:245], v[66:67]
	v_pk_mul_f32 v[68:69], v[238:239], v[68:69] op_sel:[0,1] op_sel_hi:[1,0]
	v_pk_mul_f32 v[70:71], v[240:241], v[70:71] op_sel:[0,1] op_sel_hi:[1,0]
	v_pk_mul_f32 v[64:65], v[242:243], v[64:65] op_sel:[0,1] op_sel_hi:[1,0]
	v_pk_mul_f32 v[66:67], v[244:245], v[66:67] op_sel:[0,1] op_sel_hi:[1,0]
	v_sub_f32_e32 v250, v250, v251
	v_add_f32_e32 v68, v68, v69
	v_sub_f32_e32 v252, v252, v253
	v_add_f32_e32 v70, v70, v71
	v_sub_f32_e32 v254, v254, v255
	v_add_f32_e32 v64, v64, v65
	v_sub_f32_e32 v232, v232, v233
	v_add_f32_e32 v66, v66, v67
	v_cvt_pk_bf16_f32 v68, v250, v68
	v_cvt_pk_bf16_f32 v69, v252, v70
	v_cvt_pk_bf16_f32 v70, v254, v64
	v_cvt_pk_bf16_f32 v71, v232, v66
	global_store_dwordx4 v196, v[68:71], s[54:55] offset:256
	s_mov_b64 s[6:7], 0xb000
	v_lshl_add_u64 v[144:145], v[142:143], 0, s[6:7]
	global_load_dwordx4 v[238:241], v[144:145], off
	global_load_dwordx4 v[242:245], v[144:145], off offset:16
	s_mul_i32 s61, s16, 8
	v_add_u32_e32 v236, s61, v249
	s_waitcnt vmcnt(12)
	v_pk_mul_f32 v[60:61], v[60:61], v[170:171] op_sel_hi:[1,0]
	v_pk_mul_f32 v[62:63], v[62:63], v[170:171] op_sel_hi:[1,0]
	v_pk_mul_f32 v[56:57], v[56:57], v[170:171] op_sel_hi:[1,0]
	v_pk_mul_f32 v[58:59], v[58:59], v[170:171] op_sel_hi:[1,0]
	v_pk_mul_f32 v[250:251], v[178:179], v[60:61]
	v_pk_mul_f32 v[252:253], v[180:181], v[62:63]
	v_pk_mul_f32 v[254:255], v[182:183], v[56:57]
	v_pk_mul_f32 v[232:233], v[184:185], v[58:59]
	v_pk_mul_f32 v[60:61], v[178:179], v[60:61] op_sel:[0,1] op_sel_hi:[1,0]
	v_pk_mul_f32 v[62:63], v[180:181], v[62:63] op_sel:[0,1] op_sel_hi:[1,0]
	v_pk_mul_f32 v[56:57], v[182:183], v[56:57] op_sel:[0,1] op_sel_hi:[1,0]
	v_pk_mul_f32 v[58:59], v[184:185], v[58:59] op_sel:[0,1] op_sel_hi:[1,0]
	v_sub_f32_e32 v250, v250, v251
	v_add_f32_e32 v60, v60, v61
	v_sub_f32_e32 v252, v252, v253
	v_add_f32_e32 v62, v62, v63
	v_sub_f32_e32 v254, v254, v255
	v_add_f32_e32 v56, v56, v57
	v_sub_f32_e32 v232, v232, v233
	v_add_f32_e32 v58, v58, v59
	v_cvt_pk_bf16_f32 v60, v250, v60
	v_cvt_pk_bf16_f32 v61, v252, v62
	v_cvt_pk_bf16_f32 v62, v254, v56
	v_cvt_pk_bf16_f32 v63, v232, v58
	global_store_dwordx4 v236, v[60:63], s[54:55]
	v_pk_mul_f32 v[52:53], v[52:53], v[170:171] op_sel_hi:[1,0]
	v_pk_mul_f32 v[54:55], v[54:55], v[170:171] op_sel_hi:[1,0]
	v_pk_mul_f32 v[48:49], v[48:49], v[170:171] op_sel_hi:[1,0]
	v_pk_mul_f32 v[50:51], v[50:51], v[170:171] op_sel_hi:[1,0]
	v_pk_mul_f32 v[250:251], v[178:179], v[52:53]
	v_pk_mul_f32 v[252:253], v[180:181], v[54:55]
	v_pk_mul_f32 v[254:255], v[182:183], v[48:49]
	v_pk_mul_f32 v[232:233], v[184:185], v[50:51]
	v_pk_mul_f32 v[52:53], v[178:179], v[52:53] op_sel:[0,1] op_sel_hi:[1,0]
	v_pk_mul_f32 v[54:55], v[180:181], v[54:55] op_sel:[0,1] op_sel_hi:[1,0]
	v_pk_mul_f32 v[48:49], v[182:183], v[48:49] op_sel:[0,1] op_sel_hi:[1,0]
	v_pk_mul_f32 v[50:51], v[184:185], v[50:51] op_sel:[0,1] op_sel_hi:[1,0]
	v_sub_f32_e32 v250, v250, v251
	v_add_f32_e32 v52, v52, v53
	v_sub_f32_e32 v252, v252, v253
	v_add_f32_e32 v54, v54, v55
	v_sub_f32_e32 v254, v254, v255
	v_add_f32_e32 v48, v48, v49
	v_sub_f32_e32 v232, v232, v233
	v_add_f32_e32 v50, v50, v51
	v_cvt_pk_bf16_f32 v52, v250, v52
	v_cvt_pk_bf16_f32 v53, v252, v54
	v_cvt_pk_bf16_f32 v54, v254, v48
	v_cvt_pk_bf16_f32 v55, v232, v50
	global_store_dwordx4 v236, v[52:55], s[54:55] offset:256
	s_mul_i32 s61, s16, 9
	v_add_u32_e32 v194, s61, v249
	s_waitcnt vmcnt(10)
	v_pk_mul_f32 v[44:45], v[44:45], v[172:173] op_sel_hi:[1,0]
	v_pk_mul_f32 v[46:47], v[46:47], v[172:173] op_sel_hi:[1,0]
	v_pk_mul_f32 v[40:41], v[40:41], v[172:173] op_sel_hi:[1,0]
	v_pk_mul_f32 v[42:43], v[42:43], v[172:173] op_sel_hi:[1,0]
	v_pk_mul_f32 v[250:251], v[204:205], v[44:45]
	v_pk_mul_f32 v[252:253], v[206:207], v[46:47]
	v_pk_mul_f32 v[254:255], v[208:209], v[40:41]
	v_pk_mul_f32 v[232:233], v[210:211], v[42:43]
	v_pk_mul_f32 v[44:45], v[204:205], v[44:45] op_sel:[0,1] op_sel_hi:[1,0]
	v_pk_mul_f32 v[46:47], v[206:207], v[46:47] op_sel:[0,1] op_sel_hi:[1,0]
	v_pk_mul_f32 v[40:41], v[208:209], v[40:41] op_sel:[0,1] op_sel_hi:[1,0]
	v_pk_mul_f32 v[42:43], v[210:211], v[42:43] op_sel:[0,1] op_sel_hi:[1,0]
	v_sub_f32_e32 v250, v250, v251
	v_add_f32_e32 v44, v44, v45
	v_sub_f32_e32 v252, v252, v253
	v_add_f32_e32 v46, v46, v47
	v_sub_f32_e32 v254, v254, v255
	v_add_f32_e32 v40, v40, v41
	v_sub_f32_e32 v232, v232, v233
	v_add_f32_e32 v42, v42, v43
	v_cvt_pk_bf16_f32 v44, v250, v44
	v_cvt_pk_bf16_f32 v45, v252, v46
	v_cvt_pk_bf16_f32 v46, v254, v40
	v_cvt_pk_bf16_f32 v47, v232, v42
	global_store_dwordx4 v194, v[44:47], s[54:55]
	v_pk_mul_f32 v[36:37], v[36:37], v[172:173] op_sel_hi:[1,0]
	v_pk_mul_f32 v[38:39], v[38:39], v[172:173] op_sel_hi:[1,0]
	v_pk_mul_f32 v[32:33], v[32:33], v[172:173] op_sel_hi:[1,0]
	v_pk_mul_f32 v[34:35], v[34:35], v[172:173] op_sel_hi:[1,0]
	v_pk_mul_f32 v[250:251], v[204:205], v[36:37]
	v_pk_mul_f32 v[252:253], v[206:207], v[38:39]
	v_pk_mul_f32 v[254:255], v[208:209], v[32:33]
	v_pk_mul_f32 v[232:233], v[210:211], v[34:35]
	v_pk_mul_f32 v[36:37], v[204:205], v[36:37] op_sel:[0,1] op_sel_hi:[1,0]
	v_pk_mul_f32 v[38:39], v[206:207], v[38:39] op_sel:[0,1] op_sel_hi:[1,0]
	v_pk_mul_f32 v[32:33], v[208:209], v[32:33] op_sel:[0,1] op_sel_hi:[1,0]
	v_pk_mul_f32 v[34:35], v[210:211], v[34:35] op_sel:[0,1] op_sel_hi:[1,0]
	v_sub_f32_e32 v250, v250, v251
	v_add_f32_e32 v36, v36, v37
	v_sub_f32_e32 v252, v252, v253
	v_add_f32_e32 v38, v38, v39
	v_sub_f32_e32 v254, v254, v255
	v_add_f32_e32 v32, v32, v33
	v_sub_f32_e32 v232, v232, v233
	v_add_f32_e32 v34, v34, v35
	v_cvt_pk_bf16_f32 v36, v250, v36
	v_cvt_pk_bf16_f32 v37, v252, v38
	v_cvt_pk_bf16_f32 v38, v254, v32
	v_cvt_pk_bf16_f32 v39, v232, v34
	global_store_dwordx4 v194, v[36:39], s[54:55] offset:256
	s_mul_i32 s61, s16, 10
	v_add_u32_e32 v195, s61, v249
	s_waitcnt vmcnt(8)
	v_pk_mul_f32 v[28:29], v[28:29], v[174:175] op_sel_hi:[1,0]
	v_pk_mul_f32 v[30:31], v[30:31], v[174:175] op_sel_hi:[1,0]
	v_pk_mul_f32 v[24:25], v[24:25], v[174:175] op_sel_hi:[1,0]
	v_pk_mul_f32 v[26:27], v[26:27], v[174:175] op_sel_hi:[1,0]
	v_pk_mul_f32 v[250:251], v[212:213], v[28:29]
	v_pk_mul_f32 v[252:253], v[214:215], v[30:31]
	v_pk_mul_f32 v[254:255], v[216:217], v[24:25]
	v_pk_mul_f32 v[232:233], v[218:219], v[26:27]
	v_pk_mul_f32 v[28:29], v[212:213], v[28:29] op_sel:[0,1] op_sel_hi:[1,0]
	v_pk_mul_f32 v[30:31], v[214:215], v[30:31] op_sel:[0,1] op_sel_hi:[1,0]
	v_pk_mul_f32 v[24:25], v[216:217], v[24:25] op_sel:[0,1] op_sel_hi:[1,0]
	v_pk_mul_f32 v[26:27], v[218:219], v[26:27] op_sel:[0,1] op_sel_hi:[1,0]
	v_sub_f32_e32 v250, v250, v251
	v_add_f32_e32 v28, v28, v29
	v_sub_f32_e32 v252, v252, v253
	v_add_f32_e32 v30, v30, v31
	v_sub_f32_e32 v254, v254, v255
	v_add_f32_e32 v24, v24, v25
	v_sub_f32_e32 v232, v232, v233
	v_add_f32_e32 v26, v26, v27
	v_cvt_pk_bf16_f32 v28, v250, v28
	v_cvt_pk_bf16_f32 v29, v252, v30
	v_cvt_pk_bf16_f32 v30, v254, v24
	v_cvt_pk_bf16_f32 v31, v232, v26
	global_store_dwordx4 v195, v[28:31], s[54:55]
	v_pk_mul_f32 v[20:21], v[20:21], v[174:175] op_sel_hi:[1,0]
	v_pk_mul_f32 v[22:23], v[22:23], v[174:175] op_sel_hi:[1,0]
	v_pk_mul_f32 v[16:17], v[16:17], v[174:175] op_sel_hi:[1,0]
	v_pk_mul_f32 v[18:19], v[18:19], v[174:175] op_sel_hi:[1,0]
	v_pk_mul_f32 v[250:251], v[212:213], v[20:21]
	v_pk_mul_f32 v[252:253], v[214:215], v[22:23]
	v_pk_mul_f32 v[254:255], v[216:217], v[16:17]
	v_pk_mul_f32 v[232:233], v[218:219], v[18:19]
	v_pk_mul_f32 v[20:21], v[212:213], v[20:21] op_sel:[0,1] op_sel_hi:[1,0]
	v_pk_mul_f32 v[22:23], v[214:215], v[22:23] op_sel:[0,1] op_sel_hi:[1,0]
	v_pk_mul_f32 v[16:17], v[216:217], v[16:17] op_sel:[0,1] op_sel_hi:[1,0]
	v_pk_mul_f32 v[18:19], v[218:219], v[18:19] op_sel:[0,1] op_sel_hi:[1,0]
	v_sub_f32_e32 v250, v250, v251
	v_add_f32_e32 v20, v20, v21
	v_sub_f32_e32 v252, v252, v253
	v_add_f32_e32 v22, v22, v23
	v_sub_f32_e32 v254, v254, v255
	v_add_f32_e32 v16, v16, v17
	v_sub_f32_e32 v232, v232, v233
	v_add_f32_e32 v18, v18, v19
	v_cvt_pk_bf16_f32 v20, v250, v20
	v_cvt_pk_bf16_f32 v21, v252, v22
	v_cvt_pk_bf16_f32 v22, v254, v16
	v_cvt_pk_bf16_f32 v23, v232, v18
	global_store_dwordx4 v195, v[20:23], s[54:55] offset:256
	s_mul_i32 s61, s16, 11
	v_add_u32_e32 v196, s61, v249
	s_waitcnt vmcnt(6)
	v_pk_mul_f32 v[12:13], v[12:13], v[176:177] op_sel_hi:[1,0]
	v_pk_mul_f32 v[14:15], v[14:15], v[176:177] op_sel_hi:[1,0]
	v_pk_mul_f32 v[8:9], v[8:9], v[176:177] op_sel_hi:[1,0]
	v_pk_mul_f32 v[10:11], v[10:11], v[176:177] op_sel_hi:[1,0]
	v_pk_mul_f32 v[250:251], v[238:239], v[12:13]
	v_pk_mul_f32 v[252:253], v[240:241], v[14:15]
	v_pk_mul_f32 v[254:255], v[242:243], v[8:9]
	v_pk_mul_f32 v[232:233], v[244:245], v[10:11]
	v_pk_mul_f32 v[12:13], v[238:239], v[12:13] op_sel:[0,1] op_sel_hi:[1,0]
	v_pk_mul_f32 v[14:15], v[240:241], v[14:15] op_sel:[0,1] op_sel_hi:[1,0]
	v_pk_mul_f32 v[8:9], v[242:243], v[8:9] op_sel:[0,1] op_sel_hi:[1,0]
	v_pk_mul_f32 v[10:11], v[244:245], v[10:11] op_sel:[0,1] op_sel_hi:[1,0]
	v_sub_f32_e32 v250, v250, v251
	v_add_f32_e32 v12, v12, v13
	v_sub_f32_e32 v252, v252, v253
	v_add_f32_e32 v14, v14, v15
	v_sub_f32_e32 v254, v254, v255
	v_add_f32_e32 v8, v8, v9
	v_sub_f32_e32 v232, v232, v233
	v_add_f32_e32 v10, v10, v11
	v_cvt_pk_bf16_f32 v12, v250, v12
	v_cvt_pk_bf16_f32 v13, v252, v14
	v_cvt_pk_bf16_f32 v14, v254, v8
	v_cvt_pk_bf16_f32 v15, v232, v10
	global_store_dwordx4 v196, v[12:15], s[54:55]
	v_pk_mul_f32 v[4:5], v[4:5], v[176:177] op_sel_hi:[1,0]
	v_pk_mul_f32 v[6:7], v[6:7], v[176:177] op_sel_hi:[1,0]
	v_pk_mul_f32 v[0:1], v[0:1], v[176:177] op_sel_hi:[1,0]
	v_pk_mul_f32 v[2:3], v[2:3], v[176:177] op_sel_hi:[1,0]
	v_pk_mul_f32 v[250:251], v[238:239], v[4:5]
	v_pk_mul_f32 v[252:253], v[240:241], v[6:7]
	v_pk_mul_f32 v[254:255], v[242:243], v[0:1]
	v_pk_mul_f32 v[232:233], v[244:245], v[2:3]
	v_pk_mul_f32 v[4:5], v[238:239], v[4:5] op_sel:[0,1] op_sel_hi:[1,0]
	v_pk_mul_f32 v[6:7], v[240:241], v[6:7] op_sel:[0,1] op_sel_hi:[1,0]
	v_pk_mul_f32 v[0:1], v[242:243], v[0:1] op_sel:[0,1] op_sel_hi:[1,0]
	v_pk_mul_f32 v[2:3], v[244:245], v[2:3] op_sel:[0,1] op_sel_hi:[1,0]
	v_sub_f32_e32 v250, v250, v251
	v_add_f32_e32 v4, v4, v5
	v_sub_f32_e32 v252, v252, v253
	v_add_f32_e32 v6, v6, v7
	v_sub_f32_e32 v254, v254, v255
	v_add_f32_e32 v0, v0, v1
	v_sub_f32_e32 v232, v232, v233
	v_add_f32_e32 v2, v2, v3
	v_cvt_pk_bf16_f32 v4, v250, v4
	v_cvt_pk_bf16_f32 v5, v252, v6
	v_cvt_pk_bf16_f32 v6, v254, v0
	v_cvt_pk_bf16_f32 v7, v232, v2
	global_store_dwordx4 v196, v[4:7], s[54:55] offset:256
	s_andn2_b64 vcc, exec, s[4:5]
	s_mov_b64 s[4:5], -1
	s_cbranch_vccnz .LBB0_679
	s_andn2_b64 vcc, exec, s[14:15]
	s_cbranch_vccnz .LBB0_678
	s_barrier
	s_branch .LBB0_678
